# baseline (speedup 1.0000x reference)
; DI void norm_row(const float* xrow, const float* g, bf16_t* hrow, float* xout, int lane, bool zero) {
;     const f32x4* xr = (const f32x4*)xrow + lane;
;     f32x4 v[8]; float s = 0.f;
; #pragma unroll
;     for (int j = 0; j < 8; ++j) { v[j] = zero ? (f32x4){0.f, 0.f, 0.f, 0.f} : xr[64 * j]; s += (v[j].x * v[j].x + v[j].y * v[j].y) + (v[j].z * v[j].z + v[j].w * v[j].w); }
;     s = wave_sum(s);
;     const float rstd = 1.0f / sqrtf(s * (1.0f / DM) + 1e-6f);
.LBB0_1078:
	v_lshl_add_u64 v[8:9], s[68:69], 0, v[44:45]
	v_add_co_u32_e32 v0, vcc, 0x19400000, v8
	s_mov_b32 s1, 0x19401000
	s_nop 0
	v_addc_co_u32_e32 v1, vcc, 0, v9, vcc
	v_add_co_u32_e32 v8, vcc, s1, v8
	s_mov_b32 s1, 0x1b600000
	s_nop 0
	v_addc_co_u32_e32 v9, vcc, 0, v9, vcc
	s_add_i32 s0, s0, 8
	s_cmp_lt_u32 s0, 24
	global_load_dwordx4 v[28:31], v[0:1], off
	global_load_dwordx4 v[4:7], v[0:1], off offset:1024
	global_load_dwordx4 v[12:15], v[0:1], off offset:2048
	global_load_dwordx4 v[16:19], v[8:9], off
	global_load_dwordx4 v[24:27], v[8:9], off offset:1024
	global_load_dwordx4 v[20:23], v[8:9], off offset:2048
	global_load_dwordx4 v[0:3], v[0:1], off offset:3072
	global_load_dwordx4 v[8:11], v[8:9], off offset:3072
	s_waitcnt vmcnt(0)
	v_mul_f32_e32 v54, v29, v29
	v_fma_f32 v54, v28, v28, v54
	v_mul_f32_e32 v55, v31, v31
	v_fma_f32 v55, v30, v30, v55
	v_add_f32_e32 v54, v54, v55
	v_mov_b32_e32 v46, v54
	v_mul_f32_e32 v54, v5, v5
	v_fma_f32 v54, v4, v4, v54
	v_mul_f32_e32 v55, v7, v7
	v_fma_f32 v55, v6, v6, v55
	v_add_f32_e32 v54, v54, v55
	v_add_f32_e32 v46, v46, v54
	v_mul_f32_e32 v54, v13, v13
	v_fma_f32 v54, v12, v12, v54
	v_mul_f32_e32 v55, v15, v15
	v_fma_f32 v55, v14, v14, v55
	v_add_f32_e32 v54, v54, v55
	v_add_f32_e32 v46, v46, v54
	v_mul_f32_e32 v54, v1, v1
	v_fma_f32 v54, v0, v0, v54
	v_mul_f32_e32 v55, v3, v3
	v_fma_f32 v55, v2, v2, v55
	v_add_f32_e32 v54, v54, v55
	v_add_f32_e32 v46, v46, v54
	v_mul_f32_e32 v54, v17, v17
	v_fma_f32 v54, v16, v16, v54
	v_mul_f32_e32 v55, v19, v19
	v_fma_f32 v55, v18, v18, v55
	v_add_f32_e32 v54, v54, v55
	v_add_f32_e32 v46, v46, v54
	v_mul_f32_e32 v54, v25, v25
	v_fma_f32 v54, v24, v24, v54
	v_mul_f32_e32 v55, v27, v27
	v_fma_f32 v55, v26, v26, v55
	v_add_f32_e32 v54, v54, v55
	v_add_f32_e32 v46, v46, v54
	v_mul_f32_e32 v54, v21, v21
	v_fma_f32 v54, v20, v20, v54
	v_mul_f32_e32 v55, v23, v23
	v_fma_f32 v55, v22, v22, v55
	v_add_f32_e32 v54, v54, v55
	v_add_f32_e32 v46, v46, v54
	v_mul_f32_e32 v54, v9, v9
	v_fma_f32 v54, v8, v8, v54
	v_mul_f32_e32 v55, v11, v11
	v_fma_f32 v55, v10, v10, v55
	v_add_f32_e32 v54, v54, v55
	v_add_f32_e32 v46, v46, v54
	ds_bpermute_b32 v53, v47, v46
	s_waitcnt lgkmcnt(0)
	v_add_f32_e32 v46, v46, v53
	ds_bpermute_b32 v53, v48, v46
	s_waitcnt lgkmcnt(0)
	v_add_f32_e32 v46, v46, v53
	ds_bpermute_b32 v53, v49, v46
	s_waitcnt lgkmcnt(0)
	v_add_f32_e32 v46, v46, v53
	ds_bpermute_b32 v53, v50, v46
	s_waitcnt lgkmcnt(0)
	v_add_f32_e32 v46, v46, v53
	ds_bpermute_b32 v53, v51, v46
	s_waitcnt lgkmcnt(0)
	v_add_f32_e32 v46, v46, v53
	ds_bpermute_b32 v53, v52, v46
	s_waitcnt lgkmcnt(0)
	v_add_f32_e32 v46, v46, v53
	v_fmamk_f32 v46, v46, 0x3a000000, v242
	v_cmp_gt_f32_e32 vcc, s33, v46
	v_mul_f32_e32 v53, 0x4f800000, v46
	s_nop 0
	v_cndmask_b32_e32 v46, v46, v53, vcc
	v_sqrt_f32_e32 v53, v46
	s_nop 0
	v_add_u32_e32 v54, -1, v53
	v_fma_f32 v55, -v54, v53, v46
	v_cmp_ge_f32_e64 s[36:37], 0, v55
	v_add_u32_e32 v55, 1, v53
	s_nop 0
	v_cndmask_b32_e64 v54, v53, v54, s[36:37]
	v_fma_f32 v53, -v55, v53, v46
	v_cmp_lt_f32_e64 s[36:37], 0, v53
	s_nop 1
	v_cndmask_b32_e64 v53, v54, v55, s[36:37]
	v_mul_f32_e32 v54, 0x37800000, v53
	v_cndmask_b32_e32 v53, v53, v54, vcc
	v_cmp_class_f32_e32 vcc, v46, v243
	s_nop 1
	v_cndmask_b32_e32 v46, v53, v46, vcc
	v_div_scale_f32 v53, s[6:7], v46, v46, 1.0
	v_rcp_f32_e32 v54, v53
	s_mov_b64 s[6:7], 0x10000
	v_lshl_add_u64 v[44:45], v[44:45], 0, s[6:7]
	v_fma_f32 v55, -v53, v54, 1.0
	v_fmac_f32_e32 v54, v55, v54
	v_div_scale_f32 v55, vcc, 1.0, v46, 1.0
	v_mul_f32_e32 v56, v55, v54
	v_fma_f32 v57, -v53, v56, v55
	v_fmac_f32_e32 v56, v57, v54
	v_fma_f32 v53, -v53, v56, v55
	v_div_fmas_f32 v53, v53, v54, v56
	s_nop 1
	v_mov_b64_e32 v[54:55], v[64:65]
	v_mov_b64_e32 v[56:57], v[66:67]
	v_div_fixup_f32 v46, v53, v46, 1.0
	v_pk_mul_f32 v[28:29], v[28:29], v[46:47] op_sel_hi:[1,0]
	v_pk_mul_f32 v[30:31], v[30:31], v[46:47] op_sel_hi:[1,0]
	v_pk_mul_f32 v[4:5], v[4:5], v[46:47] op_sel_hi:[1,0]
	v_pk_mul_f32 v[6:7], v[6:7], v[46:47] op_sel_hi:[1,0]
	v_pk_mul_f32 v[12:13], v[12:13], v[46:47] op_sel_hi:[1,0]
	v_pk_mul_f32 v[14:15], v[14:15], v[46:47] op_sel_hi:[1,0]
	v_pk_mul_f32 v[0:1], v[0:1], v[46:47] op_sel_hi:[1,0]
	v_pk_mul_f32 v[2:3], v[2:3], v[46:47] op_sel_hi:[1,0]
	v_pk_mul_f32 v[28:29], v[54:55], v[28:29]
	v_pk_mul_f32 v[56:57], v[56:57], v[30:31]
	v_cvt_pk_bf16_f32 v30, v28, v29
	v_lshl_add_u64 v[28:29], s[68:69], 0, v[42:43]
	v_add_co_u32_e32 v28, vcc, s1, v28
	v_cvt_pk_bf16_f32 v31, v56, v57
	s_nop 0
	v_addc_co_u32_e32 v29, vcc, 0, v29, vcc
	global_store_dwordx2 v[28:29], v[30:31], off
	s_nop 1
	v_mov_b64_e32 v[54:55], v[68:69]
	v_mov_b64_e32 v[56:57], v[70:71]
	v_lshl_add_u64 v[42:43], v[42:43], 0, s[14:15]
	v_pk_mul_f32 v[6:7], v[56:57], v[6:7]
	v_pk_mul_f32 v[4:5], v[54:55], v[4:5]
	s_nop 0
	v_cvt_pk_bf16_f32 v4, v4, v5
	v_cvt_pk_bf16_f32 v5, v6, v7
	global_store_dwordx2 v[28:29], v[4:5], off offset:512
	s_nop 1
	v_mov_b64_e32 v[4:5], v[72:73]
	v_mov_b64_e32 v[6:7], v[74:75]
	v_pk_mul_f32 v[6:7], v[6:7], v[14:15]
	v_pk_mul_f32 v[4:5], v[4:5], v[12:13]
	s_nop 0
	v_cvt_pk_bf16_f32 v4, v4, v5
	v_cvt_pk_bf16_f32 v5, v6, v7
	global_store_dwordx2 v[28:29], v[4:5], off offset:1024
	s_nop 1
	v_mov_b64_e32 v[4:5], v[76:77]
	v_mov_b64_e32 v[6:7], v[78:79]
	v_pk_mul_f32 v[2:3], v[6:7], v[2:3]
	v_pk_mul_f32 v[0:1], v[4:5], v[0:1]
	v_pk_mul_f32 v[4:5], v[16:17], v[46:47] op_sel_hi:[1,0]
	v_cvt_pk_bf16_f32 v0, v0, v1
	v_cvt_pk_bf16_f32 v1, v2, v3
	global_store_dwordx2 v[28:29], v[0:1], off offset:1536
	s_nop 1
	v_mov_b64_e32 v[0:1], v[80:81]
	v_mov_b64_e32 v[2:3], v[82:83]
	v_pk_mul_f32 v[6:7], v[18:19], v[46:47] op_sel_hi:[1,0]
	v_pk_mul_f32 v[0:1], v[0:1], v[4:5]
	v_pk_mul_f32 v[2:3], v[2:3], v[6:7]
	v_cvt_pk_bf16_f32 v0, v0, v1
	v_cvt_pk_bf16_f32 v1, v2, v3
	global_store_dwordx2 v[28:29], v[0:1], off offset:2048
	s_nop 1
	v_mov_b64_e32 v[0:1], v[84:85]
	v_mov_b64_e32 v[2:3], v[86:87]
	v_pk_mul_f32 v[4:5], v[24:25], v[46:47] op_sel_hi:[1,0]
	v_pk_mul_f32 v[6:7], v[26:27], v[46:47] op_sel_hi:[1,0]
	v_pk_mul_f32 v[0:1], v[0:1], v[4:5]
	v_pk_mul_f32 v[2:3], v[2:3], v[6:7]
	v_cvt_pk_bf16_f32 v0, v0, v1
	v_cvt_pk_bf16_f32 v1, v2, v3
	global_store_dwordx2 v[28:29], v[0:1], off offset:2560
	s_nop 1
	v_mov_b64_e32 v[0:1], v[88:89]
	v_mov_b64_e32 v[2:3], v[90:91]
	v_pk_mul_f32 v[4:5], v[20:21], v[46:47] op_sel_hi:[1,0]
	v_pk_mul_f32 v[6:7], v[22:23], v[46:47] op_sel_hi:[1,0]
	v_pk_mul_f32 v[0:1], v[4:5], v[0:1]
	v_pk_mul_f32 v[2:3], v[6:7], v[2:3]
	v_cvt_pk_bf16_f32 v0, v0, v1
	v_cvt_pk_bf16_f32 v1, v2, v3
	global_store_dwordx2 v[28:29], v[0:1], off offset:3072
	s_nop 1
	v_mov_b64_e32 v[0:1], v[92:93]
	v_mov_b64_e32 v[2:3], v[94:95]
	v_pk_mul_f32 v[4:5], v[8:9], v[46:47] op_sel_hi:[1,0]
	v_pk_mul_f32 v[6:7], v[10:11], v[46:47] op_sel_hi:[1,0]
	v_pk_mul_f32 v[0:1], v[4:5], v[0:1]
	v_pk_mul_f32 v[2:3], v[6:7], v[2:3]
	v_cvt_pk_bf16_f32 v0, v0, v1
	v_cvt_pk_bf16_f32 v1, v2, v3
	global_store_dwordx2 v[28:29], v[0:1], off offset:3584
	s_cbranch_scc1 .LBB0_1078
